# G1/G4 steady-state loops: one workgroup barrier per slice; waves 4-7 run the same instruction stream with their barrier half a slice later (rotated loop) instead of a second mid-slice barrier
# speedup vs baseline: 1.0094x; 1.0057x over previous
.LBB0_181:
	s_or_b64 exec, exec, s[20:21]
	v_mov_b32_e32 v2, 0
	v_add_u32_e32 v230, 0x1000, v201
	s_mov_b32 s19, 0
	s_mov_b64 s[20:21], 0
	s_mov_b32 s31, 0x18000
	v_mov_b32_e32 v3, v2
	v_cmp_lt_i32_e32 vcc, 3, v197
	s_cbranch_vccnz .Lgr_G4x_entry
	s_branch .Lgf_G4x_top
.Lgf_G4x_top:
	s_waitcnt vmcnt(4)
	s_waitcnt lgkmcnt(0)
	s_barrier
	v_mfma_f32_16x16x32_bf16 v[158:161], v[122:125], v[150:153], v[158:161]
	v_mfma_f32_16x16x32_bf16 v[94:97], v[126:129], v[150:153], v[94:97]
	s_add_i32 s28, s31, 0xfffe8000
	s_and_b32 s34, s28, 0x10000
	v_add_u32_e32 v170, s34, v230
	ds_read_b128 v[162:165], v170
	v_mfma_f32_16x16x32_bf16 v[62:65], v[130:133], v[150:153], v[62:65]
	ds_read_b128 v[166:169], v170 offset:1024
	v_mfma_f32_16x16x32_bf16 v[30:33], v[134:137], v[150:153], v[30:33]
	ds_read_b128 v[232:235], v170 offset:2048
	v_mfma_f32_16x16x32_bf16 v[118:121], v[122:125], v[146:149], v[118:121]
	ds_read_b128 v[236:239], v170 offset:3072
	s_and_b32 s89, s31, 0x18000
	s_add_i32 s89, s89, s88
	s_mov_b32 m0, s89
	v_mfma_f32_16x16x32_bf16 v[86:89], v[126:129], v[146:149], v[86:89]
	v_mfma_f32_16x16x32_bf16 v[54:57], v[130:133], v[146:149], v[54:57]
	global_load_lds_dwordx4 v186, s[90:91]
	s_add_i32 m0, s89, 0x2000
	v_mfma_f32_16x16x32_bf16 v[22:25], v[134:137], v[146:149], v[22:25]
	v_mfma_f32_16x16x32_bf16 v[110:113], v[122:125], v[142:145], v[110:113]
	v_mfma_f32_16x16x32_bf16 v[78:81], v[126:129], v[142:145], v[78:81]
	global_load_lds_dwordx4 v188, s[90:91]
	s_add_i32 m0, s89, 0x4000
	v_mfma_f32_16x16x32_bf16 v[46:49], v[130:133], v[142:145], v[46:49]
	v_mfma_f32_16x16x32_bf16 v[14:17], v[134:137], v[142:145], v[14:17]
	global_load_lds_dwordx4 v190, s[92:93]
	s_add_i32 m0, s89, 0x6000
	v_mfma_f32_16x16x32_bf16 v[102:105], v[122:125], v[138:141], v[102:105]
	v_mfma_f32_16x16x32_bf16 v[70:73], v[126:129], v[138:141], v[70:73]
	global_load_lds_dwordx4 v192, s[92:93]
	s_add_u32 s90, s90, 64
	s_addc_u32 s91, s91, 0
	s_add_u32 s92, s92, 64
	s_addc_u32 s93, s93, 0
	v_mfma_f32_16x16x32_bf16 v[38:41], v[130:133], v[138:141], v[38:41]
	v_mfma_f32_16x16x32_bf16 v[6:9], v[134:137], v[138:141], v[6:9]
	s_waitcnt lgkmcnt(0)
	v_mfma_f32_16x16x32_bf16 v[154:157], v[122:125], v[162:165], v[154:157]
	s_add_i32 s28, s31, 0xffff0000
	s_and_b32 s35, s28, 0x18000
	v_add_u32_e32 v187, s35, v200
	v_add_u32_e32 v226, s35, v201
	ds_read_b128 v[150:153], v226
	v_mfma_f32_16x16x32_bf16 v[90:93], v[126:129], v[162:165], v[90:93]
	ds_read_b128 v[146:149], v226 offset:1024
	v_mfma_f32_16x16x32_bf16 v[58:61], v[130:133], v[162:165], v[58:61]
	ds_read_b128 v[142:145], v226 offset:2048
	v_mfma_f32_16x16x32_bf16 v[26:29], v[134:137], v[162:165], v[26:29]
	ds_read_b128 v[138:141], v226 offset:3072
	v_mfma_f32_16x16x32_bf16 v[114:117], v[122:125], v[166:169], v[114:117]
	ds_read_b128 v[174:177], v187
	v_mfma_f32_16x16x32_bf16 v[82:85], v[126:129], v[166:169], v[82:85]
	ds_read_b128 v[170:173], v187 offset:1024
	v_mfma_f32_16x16x32_bf16 v[50:53], v[130:133], v[166:169], v[50:53]
	ds_read_b128 v[162:165], v187 offset:3072
	v_mfma_f32_16x16x32_bf16 v[18:21], v[134:137], v[166:169], v[18:21]
	ds_read_b128 v[166:169], v187 offset:2048
	v_mfma_f32_16x16x32_bf16 v[106:109], v[122:125], v[232:235], v[106:109]
	v_mfma_f32_16x16x32_bf16 v[74:77], v[126:129], v[232:235], v[74:77]
	v_mfma_f32_16x16x32_bf16 v[42:45], v[130:133], v[232:235], v[42:45]
	v_mfma_f32_16x16x32_bf16 v[10:13], v[134:137], v[232:235], v[10:13]
	v_mfma_f32_16x16x32_bf16 v[98:101], v[122:125], v[236:239], v[98:101]
	v_mfma_f32_16x16x32_bf16 v[66:69], v[126:129], v[236:239], v[66:69]
	v_mfma_f32_16x16x32_bf16 v[34:37], v[130:133], v[236:239], v[34:37]
	v_mfma_f32_16x16x32_bf16 v[2:5], v[134:137], v[236:239], v[2:5]
	s_waitcnt vmcnt(4)
	s_waitcnt lgkmcnt(0)
	s_barrier
	v_mfma_f32_16x16x32_bf16 v[158:161], v[174:177], v[150:153], v[158:161]
	v_mfma_f32_16x16x32_bf16 v[94:97], v[170:173], v[150:153], v[94:97]
	v_add_u32_e32 v226, s35, v230
	ds_read_b128 v[232:235], v226
	v_mfma_f32_16x16x32_bf16 v[62:65], v[166:169], v[150:153], v[62:65]
	ds_read_b128 v[236:239], v226 offset:1024
	v_mfma_f32_16x16x32_bf16 v[30:33], v[162:165], v[150:153], v[30:33]
	ds_read_b128 v[182:185], v226 offset:2048
	v_mfma_f32_16x16x32_bf16 v[118:121], v[174:177], v[146:149], v[118:121]
	ds_read_b128 v[178:181], v226 offset:3072
	s_add_i32 s89, s34, s88
	s_mov_b32 m0, s89
	v_mfma_f32_16x16x32_bf16 v[86:89], v[170:173], v[146:149], v[86:89]
	v_mfma_f32_16x16x32_bf16 v[54:57], v[166:169], v[146:149], v[54:57]
	global_load_lds_dwordx4 v186, s[90:91]
	s_add_i32 m0, s89, 0x2000
	v_mfma_f32_16x16x32_bf16 v[22:25], v[162:165], v[146:149], v[22:25]
	v_mfma_f32_16x16x32_bf16 v[110:113], v[174:177], v[142:145], v[110:113]
	v_mfma_f32_16x16x32_bf16 v[78:81], v[170:173], v[142:145], v[78:81]
	global_load_lds_dwordx4 v188, s[90:91]
	s_add_i32 m0, s89, 0x4000
	v_mfma_f32_16x16x32_bf16 v[46:49], v[166:169], v[142:145], v[46:49]
	v_mfma_f32_16x16x32_bf16 v[14:17], v[162:165], v[142:145], v[14:17]
	global_load_lds_dwordx4 v190, s[92:93]
	s_add_i32 m0, s89, 0x6000
	v_mfma_f32_16x16x32_bf16 v[102:105], v[174:177], v[138:141], v[102:105]
	v_mfma_f32_16x16x32_bf16 v[70:73], v[170:173], v[138:141], v[70:73]
	global_load_lds_dwordx4 v192, s[92:93]
	s_add_u32 s90, s90, 64
	s_addc_u32 s91, s91, 0
	s_add_u32 s92, s92, 64
	s_addc_u32 s93, s93, 0
	v_mfma_f32_16x16x32_bf16 v[38:41], v[166:169], v[138:141], v[38:41]
	v_mfma_f32_16x16x32_bf16 v[6:9], v[162:165], v[138:141], v[6:9]
	s_waitcnt lgkmcnt(0)
	v_mfma_f32_16x16x32_bf16 v[154:157], v[174:177], v[232:235], v[154:157]
	s_add_i32 s24, s31, 0xffff8000
	s_and_b32 s24, s24, 0x10000
	v_add_u32_e32 v187, s24, v200
	v_add_u32_e32 v226, s24, v201
	ds_read_b128 v[150:153], v226
	v_mfma_f32_16x16x32_bf16 v[90:93], v[170:173], v[232:235], v[90:93]
	ds_read_b128 v[146:149], v226 offset:1024
	v_mfma_f32_16x16x32_bf16 v[58:61], v[166:169], v[232:235], v[58:61]
	ds_read_b128 v[142:145], v226 offset:2048
	v_mfma_f32_16x16x32_bf16 v[26:29], v[162:165], v[232:235], v[26:29]
	ds_read_b128 v[138:141], v226 offset:3072
	v_mfma_f32_16x16x32_bf16 v[114:117], v[174:177], v[236:239], v[114:117]
	ds_read_b128 v[122:125], v187
	v_mfma_f32_16x16x32_bf16 v[82:85], v[170:173], v[236:239], v[82:85]
	ds_read_b128 v[126:129], v187 offset:1024
	v_mfma_f32_16x16x32_bf16 v[50:53], v[166:169], v[236:239], v[50:53]
	ds_read_b128 v[130:133], v187 offset:2048
	v_mfma_f32_16x16x32_bf16 v[18:21], v[162:165], v[236:239], v[18:21]
	ds_read_b128 v[134:137], v187 offset:3072
	s_add_i32 s19, s19, 2
	s_add_u32 s20, s20, 0x80
	s_addc_u32 s21, s21, 0
	s_add_i32 s31, s31, 0x10000
	v_mfma_f32_16x16x32_bf16 v[106:109], v[174:177], v[182:185], v[106:109]
	v_mfma_f32_16x16x32_bf16 v[74:77], v[170:173], v[182:185], v[74:77]
	v_mfma_f32_16x16x32_bf16 v[42:45], v[166:169], v[182:185], v[42:45]
	v_mfma_f32_16x16x32_bf16 v[10:13], v[162:165], v[182:185], v[10:13]
	v_mfma_f32_16x16x32_bf16 v[98:101], v[174:177], v[178:181], v[98:101]
	v_mfma_f32_16x16x32_bf16 v[66:69], v[170:173], v[178:181], v[66:69]
	v_mfma_f32_16x16x32_bf16 v[34:37], v[166:169], v[178:181], v[34:37]
	v_mfma_f32_16x16x32_bf16 v[2:5], v[162:165], v[178:181], v[2:5]
	s_cmp_lt_u32 s19, 28
	s_cbranch_scc1 .Lgf_G4x_top
	s_branch .LBB0_183
.Lgr_G4x_entry:
	s_waitcnt vmcnt(4)
	s_waitcnt lgkmcnt(0)
	s_barrier
	v_mfma_f32_16x16x32_bf16 v[158:161], v[122:125], v[150:153], v[158:161]
	v_mfma_f32_16x16x32_bf16 v[94:97], v[126:129], v[150:153], v[94:97]
	s_add_i32 s28, s31, 0xfffe8000
	s_and_b32 s34, s28, 0x10000
	v_add_u32_e32 v170, s34, v230
	ds_read_b128 v[162:165], v170
	v_mfma_f32_16x16x32_bf16 v[62:65], v[130:133], v[150:153], v[62:65]
	ds_read_b128 v[166:169], v170 offset:1024
	v_mfma_f32_16x16x32_bf16 v[30:33], v[134:137], v[150:153], v[30:33]
	ds_read_b128 v[232:235], v170 offset:2048
	v_mfma_f32_16x16x32_bf16 v[118:121], v[122:125], v[146:149], v[118:121]
	ds_read_b128 v[236:239], v170 offset:3072
	s_and_b32 s89, s31, 0x18000
	s_add_i32 s89, s89, s88
	s_mov_b32 m0, s89
	v_mfma_f32_16x16x32_bf16 v[86:89], v[126:129], v[146:149], v[86:89]
	v_mfma_f32_16x16x32_bf16 v[54:57], v[130:133], v[146:149], v[54:57]
	global_load_lds_dwordx4 v186, s[90:91]
	s_add_i32 m0, s89, 0x2000
	v_mfma_f32_16x16x32_bf16 v[22:25], v[134:137], v[146:149], v[22:25]
	v_mfma_f32_16x16x32_bf16 v[110:113], v[122:125], v[142:145], v[110:113]
	v_mfma_f32_16x16x32_bf16 v[78:81], v[126:129], v[142:145], v[78:81]
	global_load_lds_dwordx4 v188, s[90:91]
	s_add_i32 m0, s89, 0x4000
	v_mfma_f32_16x16x32_bf16 v[46:49], v[130:133], v[142:145], v[46:49]
	v_mfma_f32_16x16x32_bf16 v[14:17], v[134:137], v[142:145], v[14:17]
	global_load_lds_dwordx4 v190, s[92:93]
	s_add_i32 m0, s89, 0x6000
	v_mfma_f32_16x16x32_bf16 v[102:105], v[122:125], v[138:141], v[102:105]
	v_mfma_f32_16x16x32_bf16 v[70:73], v[126:129], v[138:141], v[70:73]
	global_load_lds_dwordx4 v192, s[92:93]
	s_add_u32 s90, s90, 64
	s_addc_u32 s91, s91, 0
	s_add_u32 s92, s92, 64
	s_addc_u32 s93, s93, 0
	v_mfma_f32_16x16x32_bf16 v[38:41], v[130:133], v[138:141], v[38:41]
	v_mfma_f32_16x16x32_bf16 v[6:9], v[134:137], v[138:141], v[6:9]
	s_waitcnt vmcnt(4)
	s_waitcnt lgkmcnt(0)
	s_barrier
	v_mfma_f32_16x16x32_bf16 v[154:157], v[122:125], v[162:165], v[154:157]
	s_add_i32 s28, s31, 0xffff0000
	s_and_b32 s35, s28, 0x18000
	v_add_u32_e32 v187, s35, v200
	v_add_u32_e32 v226, s35, v201
	ds_read_b128 v[150:153], v226
	v_mfma_f32_16x16x32_bf16 v[90:93], v[126:129], v[162:165], v[90:93]
	ds_read_b128 v[146:149], v226 offset:1024
	v_mfma_f32_16x16x32_bf16 v[58:61], v[130:133], v[162:165], v[58:61]
	ds_read_b128 v[142:145], v226 offset:2048
	v_mfma_f32_16x16x32_bf16 v[26:29], v[134:137], v[162:165], v[26:29]
	ds_read_b128 v[138:141], v226 offset:3072
	v_mfma_f32_16x16x32_bf16 v[114:117], v[122:125], v[166:169], v[114:117]
	ds_read_b128 v[174:177], v187
	v_mfma_f32_16x16x32_bf16 v[82:85], v[126:129], v[166:169], v[82:85]
	ds_read_b128 v[170:173], v187 offset:1024
	v_mfma_f32_16x16x32_bf16 v[50:53], v[130:133], v[166:169], v[50:53]
	ds_read_b128 v[162:165], v187 offset:3072
	v_mfma_f32_16x16x32_bf16 v[18:21], v[134:137], v[166:169], v[18:21]
	ds_read_b128 v[166:169], v187 offset:2048
	v_mfma_f32_16x16x32_bf16 v[106:109], v[122:125], v[232:235], v[106:109]
	v_mfma_f32_16x16x32_bf16 v[74:77], v[126:129], v[232:235], v[74:77]
	v_mfma_f32_16x16x32_bf16 v[42:45], v[130:133], v[232:235], v[42:45]
	v_mfma_f32_16x16x32_bf16 v[10:13], v[134:137], v[232:235], v[10:13]
	v_mfma_f32_16x16x32_bf16 v[98:101], v[122:125], v[236:239], v[98:101]
	v_mfma_f32_16x16x32_bf16 v[66:69], v[126:129], v[236:239], v[66:69]
	v_mfma_f32_16x16x32_bf16 v[34:37], v[130:133], v[236:239], v[34:37]
	v_mfma_f32_16x16x32_bf16 v[2:5], v[134:137], v[236:239], v[2:5]
	s_waitcnt lgkmcnt(0)
	v_mfma_f32_16x16x32_bf16 v[158:161], v[174:177], v[150:153], v[158:161]
	v_mfma_f32_16x16x32_bf16 v[94:97], v[170:173], v[150:153], v[94:97]
	v_add_u32_e32 v226, s35, v230
	ds_read_b128 v[232:235], v226
	v_mfma_f32_16x16x32_bf16 v[62:65], v[166:169], v[150:153], v[62:65]
	ds_read_b128 v[236:239], v226 offset:1024
	v_mfma_f32_16x16x32_bf16 v[30:33], v[162:165], v[150:153], v[30:33]
	ds_read_b128 v[182:185], v226 offset:2048
	v_mfma_f32_16x16x32_bf16 v[118:121], v[174:177], v[146:149], v[118:121]
	ds_read_b128 v[178:181], v226 offset:3072
	s_add_i32 s89, s34, s88
	s_mov_b32 m0, s89
	v_mfma_f32_16x16x32_bf16 v[86:89], v[170:173], v[146:149], v[86:89]
	v_mfma_f32_16x16x32_bf16 v[54:57], v[166:169], v[146:149], v[54:57]
	global_load_lds_dwordx4 v186, s[90:91]
	s_add_i32 m0, s89, 0x2000
	v_mfma_f32_16x16x32_bf16 v[22:25], v[162:165], v[146:149], v[22:25]
	v_mfma_f32_16x16x32_bf16 v[110:113], v[174:177], v[142:145], v[110:113]
	v_mfma_f32_16x16x32_bf16 v[78:81], v[170:173], v[142:145], v[78:81]
	global_load_lds_dwordx4 v188, s[90:91]
	s_add_i32 m0, s89, 0x4000
	v_mfma_f32_16x16x32_bf16 v[46:49], v[166:169], v[142:145], v[46:49]
	v_mfma_f32_16x16x32_bf16 v[14:17], v[162:165], v[142:145], v[14:17]
	global_load_lds_dwordx4 v190, s[92:93]
	s_add_i32 m0, s89, 0x6000
	v_mfma_f32_16x16x32_bf16 v[102:105], v[174:177], v[138:141], v[102:105]
	v_mfma_f32_16x16x32_bf16 v[70:73], v[170:173], v[138:141], v[70:73]
	global_load_lds_dwordx4 v192, s[92:93]
	s_add_u32 s90, s90, 64
	s_addc_u32 s91, s91, 0
	s_add_u32 s92, s92, 64
	s_addc_u32 s93, s93, 0
	v_mfma_f32_16x16x32_bf16 v[38:41], v[166:169], v[138:141], v[38:41]
	v_mfma_f32_16x16x32_bf16 v[6:9], v[162:165], v[138:141], v[6:9]
.Lgr_G4x_top:
	s_waitcnt vmcnt(4)
	s_waitcnt lgkmcnt(0)
	s_barrier
	v_mfma_f32_16x16x32_bf16 v[154:157], v[174:177], v[232:235], v[154:157]
	s_add_i32 s24, s31, 0xffff8000
	s_and_b32 s24, s24, 0x10000
	v_add_u32_e32 v187, s24, v200
	v_add_u32_e32 v226, s24, v201
	ds_read_b128 v[150:153], v226
	v_mfma_f32_16x16x32_bf16 v[90:93], v[170:173], v[232:235], v[90:93]
	ds_read_b128 v[146:149], v226 offset:1024
	v_mfma_f32_16x16x32_bf16 v[58:61], v[166:169], v[232:235], v[58:61]
	ds_read_b128 v[142:145], v226 offset:2048
	v_mfma_f32_16x16x32_bf16 v[26:29], v[162:165], v[232:235], v[26:29]
	ds_read_b128 v[138:141], v226 offset:3072
	v_mfma_f32_16x16x32_bf16 v[114:117], v[174:177], v[236:239], v[114:117]
	ds_read_b128 v[122:125], v187
	v_mfma_f32_16x16x32_bf16 v[82:85], v[170:173], v[236:239], v[82:85]
	ds_read_b128 v[126:129], v187 offset:1024
	v_mfma_f32_16x16x32_bf16 v[50:53], v[166:169], v[236:239], v[50:53]
	ds_read_b128 v[130:133], v187 offset:2048
	v_mfma_f32_16x16x32_bf16 v[18:21], v[162:165], v[236:239], v[18:21]
	ds_read_b128 v[134:137], v187 offset:3072
	s_add_i32 s19, s19, 2
	s_add_u32 s20, s20, 0x80
	s_addc_u32 s21, s21, 0
	s_add_i32 s31, s31, 0x10000
	v_mfma_f32_16x16x32_bf16 v[106:109], v[174:177], v[182:185], v[106:109]
	v_mfma_f32_16x16x32_bf16 v[74:77], v[170:173], v[182:185], v[74:77]
	v_mfma_f32_16x16x32_bf16 v[42:45], v[166:169], v[182:185], v[42:45]
	v_mfma_f32_16x16x32_bf16 v[10:13], v[162:165], v[182:185], v[10:13]
	v_mfma_f32_16x16x32_bf16 v[98:101], v[174:177], v[178:181], v[98:101]
	v_mfma_f32_16x16x32_bf16 v[66:69], v[170:173], v[178:181], v[66:69]
	v_mfma_f32_16x16x32_bf16 v[34:37], v[166:169], v[178:181], v[34:37]
	v_mfma_f32_16x16x32_bf16 v[2:5], v[162:165], v[178:181], v[2:5]
	s_cmp_lt_u32 s19, 28
	s_cbranch_scc0 .LBB0_183
	s_waitcnt lgkmcnt(0)
	v_mfma_f32_16x16x32_bf16 v[158:161], v[122:125], v[150:153], v[158:161]
	v_mfma_f32_16x16x32_bf16 v[94:97], v[126:129], v[150:153], v[94:97]
	s_add_i32 s28, s31, 0xfffe8000
	s_and_b32 s34, s28, 0x10000
	v_add_u32_e32 v170, s34, v230
	ds_read_b128 v[162:165], v170
	v_mfma_f32_16x16x32_bf16 v[62:65], v[130:133], v[150:153], v[62:65]
	ds_read_b128 v[166:169], v170 offset:1024
	v_mfma_f32_16x16x32_bf16 v[30:33], v[134:137], v[150:153], v[30:33]
	ds_read_b128 v[232:235], v170 offset:2048
	v_mfma_f32_16x16x32_bf16 v[118:121], v[122:125], v[146:149], v[118:121]
	ds_read_b128 v[236:239], v170 offset:3072
	s_and_b32 s89, s31, 0x18000
	s_add_i32 s89, s89, s88
	s_mov_b32 m0, s89
	v_mfma_f32_16x16x32_bf16 v[86:89], v[126:129], v[146:149], v[86:89]
	v_mfma_f32_16x16x32_bf16 v[54:57], v[130:133], v[146:149], v[54:57]
	global_load_lds_dwordx4 v186, s[90:91]
	s_add_i32 m0, s89, 0x2000
	v_mfma_f32_16x16x32_bf16 v[22:25], v[134:137], v[146:149], v[22:25]
	v_mfma_f32_16x16x32_bf16 v[110:113], v[122:125], v[142:145], v[110:113]
	v_mfma_f32_16x16x32_bf16 v[78:81], v[126:129], v[142:145], v[78:81]
	global_load_lds_dwordx4 v188, s[90:91]
	s_add_i32 m0, s89, 0x4000
	v_mfma_f32_16x16x32_bf16 v[46:49], v[130:133], v[142:145], v[46:49]
	v_mfma_f32_16x16x32_bf16 v[14:17], v[134:137], v[142:145], v[14:17]
	global_load_lds_dwordx4 v190, s[92:93]
	s_add_i32 m0, s89, 0x6000
	v_mfma_f32_16x16x32_bf16 v[102:105], v[122:125], v[138:141], v[102:105]
	v_mfma_f32_16x16x32_bf16 v[70:73], v[126:129], v[138:141], v[70:73]
	global_load_lds_dwordx4 v192, s[92:93]
	s_add_u32 s90, s90, 64
	s_addc_u32 s91, s91, 0
	s_add_u32 s92, s92, 64
	s_addc_u32 s93, s93, 0
	v_mfma_f32_16x16x32_bf16 v[38:41], v[130:133], v[138:141], v[38:41]
	v_mfma_f32_16x16x32_bf16 v[6:9], v[134:137], v[138:141], v[6:9]
	s_waitcnt vmcnt(4)
	s_waitcnt lgkmcnt(0)
	s_barrier
	v_mfma_f32_16x16x32_bf16 v[154:157], v[122:125], v[162:165], v[154:157]
	s_add_i32 s28, s31, 0xffff0000
	s_and_b32 s35, s28, 0x18000
	v_add_u32_e32 v187, s35, v200
	v_add_u32_e32 v226, s35, v201
	ds_read_b128 v[150:153], v226
	v_mfma_f32_16x16x32_bf16 v[90:93], v[126:129], v[162:165], v[90:93]
	ds_read_b128 v[146:149], v226 offset:1024
	v_mfma_f32_16x16x32_bf16 v[58:61], v[130:133], v[162:165], v[58:61]
	ds_read_b128 v[142:145], v226 offset:2048
	v_mfma_f32_16x16x32_bf16 v[26:29], v[134:137], v[162:165], v[26:29]
	ds_read_b128 v[138:141], v226 offset:3072
	v_mfma_f32_16x16x32_bf16 v[114:117], v[122:125], v[166:169], v[114:117]
	ds_read_b128 v[174:177], v187
	v_mfma_f32_16x16x32_bf16 v[82:85], v[126:129], v[166:169], v[82:85]
	ds_read_b128 v[170:173], v187 offset:1024
	v_mfma_f32_16x16x32_bf16 v[50:53], v[130:133], v[166:169], v[50:53]
	ds_read_b128 v[162:165], v187 offset:3072
	v_mfma_f32_16x16x32_bf16 v[18:21], v[134:137], v[166:169], v[18:21]
	ds_read_b128 v[166:169], v187 offset:2048
	v_mfma_f32_16x16x32_bf16 v[106:109], v[122:125], v[232:235], v[106:109]
	v_mfma_f32_16x16x32_bf16 v[74:77], v[126:129], v[232:235], v[74:77]
	v_mfma_f32_16x16x32_bf16 v[42:45], v[130:133], v[232:235], v[42:45]
	v_mfma_f32_16x16x32_bf16 v[10:13], v[134:137], v[232:235], v[10:13]
	v_mfma_f32_16x16x32_bf16 v[98:101], v[122:125], v[236:239], v[98:101]
	v_mfma_f32_16x16x32_bf16 v[66:69], v[126:129], v[236:239], v[66:69]
	v_mfma_f32_16x16x32_bf16 v[34:37], v[130:133], v[236:239], v[34:37]
	v_mfma_f32_16x16x32_bf16 v[2:5], v[134:137], v[236:239], v[2:5]
	s_waitcnt lgkmcnt(0)
	v_mfma_f32_16x16x32_bf16 v[158:161], v[174:177], v[150:153], v[158:161]
	v_mfma_f32_16x16x32_bf16 v[94:97], v[170:173], v[150:153], v[94:97]
	v_add_u32_e32 v226, s35, v230
	ds_read_b128 v[232:235], v226
	v_mfma_f32_16x16x32_bf16 v[62:65], v[166:169], v[150:153], v[62:65]
	ds_read_b128 v[236:239], v226 offset:1024
	v_mfma_f32_16x16x32_bf16 v[30:33], v[162:165], v[150:153], v[30:33]
	ds_read_b128 v[182:185], v226 offset:2048
	v_mfma_f32_16x16x32_bf16 v[118:121], v[174:177], v[146:149], v[118:121]
	ds_read_b128 v[178:181], v226 offset:3072
	s_add_i32 s89, s34, s88
	s_mov_b32 m0, s89
	v_mfma_f32_16x16x32_bf16 v[86:89], v[170:173], v[146:149], v[86:89]
	v_mfma_f32_16x16x32_bf16 v[54:57], v[166:169], v[146:149], v[54:57]
	global_load_lds_dwordx4 v186, s[90:91]
	s_add_i32 m0, s89, 0x2000
	v_mfma_f32_16x16x32_bf16 v[22:25], v[162:165], v[146:149], v[22:25]
	v_mfma_f32_16x16x32_bf16 v[110:113], v[174:177], v[142:145], v[110:113]
	v_mfma_f32_16x16x32_bf16 v[78:81], v[170:173], v[142:145], v[78:81]
	global_load_lds_dwordx4 v188, s[90:91]
	s_add_i32 m0, s89, 0x4000
	v_mfma_f32_16x16x32_bf16 v[46:49], v[166:169], v[142:145], v[46:49]
	v_mfma_f32_16x16x32_bf16 v[14:17], v[162:165], v[142:145], v[14:17]
	global_load_lds_dwordx4 v190, s[92:93]
	s_add_i32 m0, s89, 0x6000
	v_mfma_f32_16x16x32_bf16 v[102:105], v[174:177], v[138:141], v[102:105]
	v_mfma_f32_16x16x32_bf16 v[70:73], v[170:173], v[138:141], v[70:73]
	global_load_lds_dwordx4 v192, s[92:93]
	s_add_u32 s90, s90, 64
	s_addc_u32 s91, s91, 0
	s_add_u32 s92, s92, 64
	s_addc_u32 s93, s93, 0
	v_mfma_f32_16x16x32_bf16 v[38:41], v[166:169], v[138:141], v[38:41]
	v_mfma_f32_16x16x32_bf16 v[6:9], v[162:165], v[138:141], v[6:9]
	s_branch .Lgr_G4x_top

.LBB0_407:
	s_or_b64 exec, exec, s[20:21]
	v_readlane_b32 s8, v254, 46
	v_mov_b32_e32 v24, v1
	v_mov_b32_e32 v25, v1
	v_lshl_add_u32 v233, v0, 6, s8
	v_lshrrev_b32_e32 v0, 4, v233
	s_movk_i32 s8, 0xc0
	v_mul_lo_u32 v238, v0, s8
	s_nop 1
	v_readfirstlane_b32 s36, v238
	v_readfirstlane_b32 s37, v231
	v_readlane_b32 s38, v254, 47
	s_nop 3
	s_lshl_b32 s37, s37, 2
	s_lshr_b32 s38, s38, 4
	s_add_i32 s36, s36, s37
	s_add_i32 s36, s36, s38
	s_lshl_b32 s36, s36, 9
	s_add_u32 s36, s46, s36
	s_addc_u32 s37, s47, 0
	v_lshlrev_b32_e32 v0, 3, v200
	v_mov_b32_e32 v22, v1
	v_mov_b32_e32 v23, v1
	v_mov_b32_e32 v30, 0
	v_mov_b32_e32 v42, 0
	v_mov_b64_e32 v[36:37], v[24:25]
	v_add_u32_e32 v237, 0x800, v236
	v_or_b32_e32 v239, 0xc0, v238
	v_add_u32_e32 v240, 0x180, v238
	v_add_u32_e32 v241, 0x240, v238
	s_mov_b32 s8, 3
	v_lshl_add_u64 v[132:133], s[46:47], 0, v[0:1]
	s_mov_b64 s[20:21], 0
	v_mov_b64_e32 v[34:35], v[22:23]
	s_branch .LBB0_409

.LBB0_409:
	s_add_i32 s17, s8, -3
	s_cmp_lt_u32 s17, 46
	s_cselect_b64 s[22:23], -1, 0
	s_and_b32 s38, s17, 15
	s_cmp_eq_u32 s38, 14
	s_cbranch_scc1 .Lg2_w2
	s_cmp_gt_u32 s17, 45
	s_cbranch_scc1 .Lg2_w0a
	s_waitcnt vmcnt(3)
.LBB0_413:
	s_waitcnt lgkmcnt(0)
	s_cmp_gt_u32 s17, 44
	s_cselect_b64 s[24:25], -1, 0
	s_and_b64 vcc, exec, s[24:25]
	s_barrier
	s_and_b32 s28, s17, 2
	s_mulk_i32 s28, 0x6000
	v_add_u32_e32 v110, s28, v237
	ds_read_b128 v[106:109], v110
	ds_read_b128 v[242:245], v110 offset:1024
	s_cbranch_vccnz .Lgm_G2x_nodma0
	s_and_b32 s89, s8, 3
	s_mulk_i32 s89, 0x6000
	s_add_i32 s89, s89, s88
	s_mov_b32 m0, s89
	v_mfma_f32_16x16x32_bf16 v[102:105], v[14:17], v[26:29], v[102:105]
	v_mfma_f32_16x16x32_bf16 v[86:89], v[10:13], v[26:29], v[86:89]
	global_load_lds_dwordx4 v126, s[90:91]
	s_add_i32 m0, s89, 0x2000
	v_mfma_f32_16x16x32_bf16 v[70:73], v[6:9], v[26:29], v[70:73]
	v_mfma_f32_16x16x32_bf16 v[54:57], v[2:5], v[26:29], v[54:57]
	global_load_lds_dwordx4 v128, s[90:91]
	s_add_i32 m0, s89, 0x4000
	v_mfma_f32_16x16x32_bf16 v[98:101], v[14:17], v[18:21], v[98:101]
	v_mfma_f32_16x16x32_bf16 v[82:85], v[10:13], v[18:21], v[82:85]
	global_load_lds_dwordx4 v130, s[92:93]
	v_mfma_f32_16x16x32_bf16 v[66:69], v[6:9], v[18:21], v[66:69]
	v_mfma_f32_16x16x32_bf16 v[50:53], v[2:5], v[18:21], v[50:53]
	s_add_u32 s90, s90, 64
	s_addc_u32 s91, s91, 0
	s_add_u32 s92, s92, 64
	s_addc_u32 s93, s93, 0
	s_and_b32 s38, s17, 15
	s_cmp_eq_u32 s38, 12
	s_cbranch_scc1 .Lg2_gates
.LBB0_415:
	s_waitcnt lgkmcnt(0)
	s_barrier
	s_add_i32 s19, s8, -2
	s_and_b32 s29, s19, 3
	s_mulk_i32 s29, 0x6000
	v_add_u32_e32 v127, s29, v235
	v_add_u32_e32 v131, s29, v236
	ds_read_b128 v[26:29], v131
	v_mfma_f32_16x16x32_bf16 v[90:93], v[14:17], v[106:109], v[90:93]
	ds_read_b128 v[18:21], v131 offset:1024
	v_mfma_f32_16x16x32_bf16 v[74:77], v[10:13], v[106:109], v[74:77]
	ds_read_b128 v[118:121], v127
	v_mfma_f32_16x16x32_bf16 v[58:61], v[6:9], v[106:109], v[58:61]
	ds_read_b128 v[114:117], v127 offset:1024
	v_mfma_f32_16x16x32_bf16 v[46:49], v[2:5], v[106:109], v[46:49]
	ds_read_b128 v[110:113], v127 offset:2048
	ds_read_b128 v[106:109], v127 offset:3072
	v_mfma_f32_16x16x32_bf16 v[94:97], v[14:17], v[242:245], v[94:97]
	v_mfma_f32_16x16x32_bf16 v[78:81], v[10:13], v[242:245], v[78:81]
	v_mfma_f32_16x16x32_bf16 v[62:65], v[6:9], v[242:245], v[62:65]
	v_mfma_f32_16x16x32_bf16 v[42:45], v[2:5], v[242:245], v[42:45]
	s_and_b32 s38, s17, 15
	s_cmp_eq_u32 s38, 12
	s_cbranch_scc1 .Lg2_w1
	s_and_b64 vcc, exec, s[24:25]
	s_cbranch_vccnz .Lg2_w0b
	s_waitcnt vmcnt(3)

.LBB0_643:
	s_or_b64 exec, exec, s[20:21]
	v_mov_b32_e32 v2, 0
	v_add_u32_e32 v233, 0x1000, v232
	s_mov_b32 s30, 0
	s_mov_b64 s[20:21], 0
	s_mov_b32 s31, 0x18000
	v_mov_b32_e32 v3, v2
	v_cmp_lt_i32_e32 vcc, 3, v187
	s_cbranch_vccnz .Lgr_G1x_entry
	s_branch .Lgf_G1x_top
.Lgf_G1x_top:
	s_waitcnt vmcnt(4)
	s_waitcnt lgkmcnt(0)
	s_barrier
	v_mfma_f32_16x16x32_bf16 v[126:129], v[130:133], v[158:161], v[126:129]
	v_mfma_f32_16x16x32_bf16 v[98:101], v[134:137], v[158:161], v[98:101]
	s_add_i32 s28, s31, 0xfffe8000
	s_and_b32 s34, s28, 0x10000
	v_add_u32_e32 v170, s34, v233
	ds_read_b128 v[162:165], v170
	v_mfma_f32_16x16x32_bf16 v[66:69], v[138:141], v[158:161], v[66:69]
	ds_read_b128 v[166:169], v170 offset:1024
	v_mfma_f32_16x16x32_bf16 v[34:37], v[142:145], v[158:161], v[34:37]
	ds_read_b128 v[234:237], v170 offset:2048
	v_mfma_f32_16x16x32_bf16 v[122:125], v[130:133], v[154:157], v[122:125]
	ds_read_b128 v[238:241], v170 offset:3072
	s_and_b32 s40, s31, 0x18000
	s_add_i32 s40, s40, s69
	s_mov_b32 m0, s40
	v_mfma_f32_16x16x32_bf16 v[90:93], v[134:137], v[154:157], v[90:93]
	v_mfma_f32_16x16x32_bf16 v[58:61], v[138:141], v[154:157], v[58:61]
	global_load_lds_dwordx4 v188, s[94:95]
	s_add_i32 m0, s40, 0x2000
	v_mfma_f32_16x16x32_bf16 v[26:29], v[142:145], v[154:157], v[26:29]
	v_mfma_f32_16x16x32_bf16 v[118:121], v[130:133], v[150:153], v[118:121]
	v_mfma_f32_16x16x32_bf16 v[86:89], v[134:137], v[150:153], v[86:89]
	global_load_lds_dwordx4 v190, s[94:95]
	s_add_i32 m0, s40, 0x4000
	v_mfma_f32_16x16x32_bf16 v[54:57], v[138:141], v[150:153], v[54:57]
	v_mfma_f32_16x16x32_bf16 v[22:25], v[142:145], v[150:153], v[22:25]
	global_load_lds_dwordx4 v192, s[42:43]
	s_add_i32 m0, s40, 0x6000
	v_mfma_f32_16x16x32_bf16 v[114:117], v[130:133], v[146:149], v[114:117]
	v_mfma_f32_16x16x32_bf16 v[82:85], v[134:137], v[146:149], v[82:85]
	global_load_lds_dwordx4 v194, s[42:43]
	s_add_u32 s94, s94, 64
	s_addc_u32 s95, s95, 0
	s_add_u32 s42, s42, 64
	s_addc_u32 s43, s43, 0
	v_mfma_f32_16x16x32_bf16 v[50:53], v[138:141], v[146:149], v[50:53]
	v_mfma_f32_16x16x32_bf16 v[18:21], v[142:145], v[146:149], v[18:21]
	s_waitcnt lgkmcnt(0)
	v_mfma_f32_16x16x32_bf16 v[110:113], v[130:133], v[162:165], v[110:113]
	s_add_i32 s28, s31, 0xffff0000
	s_and_b32 s35, s28, 0x18000
	v_add_u32_e32 v189, s35, v231
	v_add_u32_e32 v226, s35, v232
	ds_read_b128 v[158:161], v226
	v_mfma_f32_16x16x32_bf16 v[78:81], v[134:137], v[162:165], v[78:81]
	ds_read_b128 v[154:157], v226 offset:1024
	v_mfma_f32_16x16x32_bf16 v[46:49], v[138:141], v[162:165], v[46:49]
	ds_read_b128 v[150:153], v226 offset:2048
	v_mfma_f32_16x16x32_bf16 v[14:17], v[142:145], v[162:165], v[14:17]
	ds_read_b128 v[146:149], v226 offset:3072
	v_mfma_f32_16x16x32_bf16 v[106:109], v[130:133], v[166:169], v[106:109]
	ds_read_b128 v[174:177], v189
	v_mfma_f32_16x16x32_bf16 v[74:77], v[134:137], v[166:169], v[74:77]
	ds_read_b128 v[170:173], v189 offset:1024
	v_mfma_f32_16x16x32_bf16 v[42:45], v[138:141], v[166:169], v[42:45]
	ds_read_b128 v[162:165], v189 offset:3072
	v_mfma_f32_16x16x32_bf16 v[10:13], v[142:145], v[166:169], v[10:13]
	ds_read_b128 v[166:169], v189 offset:2048
	v_mfma_f32_16x16x32_bf16 v[102:105], v[130:133], v[234:237], v[102:105]
	v_mfma_f32_16x16x32_bf16 v[70:73], v[134:137], v[234:237], v[70:73]
	v_mfma_f32_16x16x32_bf16 v[38:41], v[138:141], v[234:237], v[38:41]
	v_mfma_f32_16x16x32_bf16 v[6:9], v[142:145], v[234:237], v[6:9]
	v_mfma_f32_16x16x32_bf16 v[94:97], v[130:133], v[238:241], v[94:97]
	v_mfma_f32_16x16x32_bf16 v[62:65], v[134:137], v[238:241], v[62:65]
	v_mfma_f32_16x16x32_bf16 v[30:33], v[138:141], v[238:241], v[30:33]
	v_mfma_f32_16x16x32_bf16 v[2:5], v[142:145], v[238:241], v[2:5]
	s_waitcnt vmcnt(4)
	s_waitcnt lgkmcnt(0)
	s_barrier
	v_mfma_f32_16x16x32_bf16 v[126:129], v[174:177], v[158:161], v[126:129]
	v_mfma_f32_16x16x32_bf16 v[98:101], v[170:173], v[158:161], v[98:101]
	v_add_u32_e32 v226, s35, v233
	ds_read_b128 v[234:237], v226
	v_mfma_f32_16x16x32_bf16 v[66:69], v[166:169], v[158:161], v[66:69]
	ds_read_b128 v[238:241], v226 offset:1024
	v_mfma_f32_16x16x32_bf16 v[34:37], v[162:165], v[158:161], v[34:37]
	ds_read_b128 v[182:185], v226 offset:2048
	v_mfma_f32_16x16x32_bf16 v[122:125], v[174:177], v[154:157], v[122:125]
	ds_read_b128 v[178:181], v226 offset:3072
	s_add_i32 s40, s34, s69
	s_mov_b32 m0, s40
	v_mfma_f32_16x16x32_bf16 v[90:93], v[170:173], v[154:157], v[90:93]
	v_mfma_f32_16x16x32_bf16 v[58:61], v[166:169], v[154:157], v[58:61]
	global_load_lds_dwordx4 v188, s[94:95]
	s_add_i32 m0, s40, 0x2000
	v_mfma_f32_16x16x32_bf16 v[26:29], v[162:165], v[154:157], v[26:29]
	v_mfma_f32_16x16x32_bf16 v[118:121], v[174:177], v[150:153], v[118:121]
	v_mfma_f32_16x16x32_bf16 v[86:89], v[170:173], v[150:153], v[86:89]
	global_load_lds_dwordx4 v190, s[94:95]
	s_add_i32 m0, s40, 0x4000
	v_mfma_f32_16x16x32_bf16 v[54:57], v[166:169], v[150:153], v[54:57]
	v_mfma_f32_16x16x32_bf16 v[22:25], v[162:165], v[150:153], v[22:25]
	global_load_lds_dwordx4 v192, s[42:43]
	s_add_i32 m0, s40, 0x6000
	v_mfma_f32_16x16x32_bf16 v[114:117], v[174:177], v[146:149], v[114:117]
	v_mfma_f32_16x16x32_bf16 v[82:85], v[170:173], v[146:149], v[82:85]
	global_load_lds_dwordx4 v194, s[42:43]
	s_add_u32 s94, s94, 64
	s_addc_u32 s95, s95, 0
	s_add_u32 s42, s42, 64
	s_addc_u32 s43, s43, 0
	v_mfma_f32_16x16x32_bf16 v[50:53], v[166:169], v[146:149], v[50:53]
	v_mfma_f32_16x16x32_bf16 v[18:21], v[162:165], v[146:149], v[18:21]
	s_waitcnt lgkmcnt(0)
	v_mfma_f32_16x16x32_bf16 v[110:113], v[174:177], v[234:237], v[110:113]
	s_add_i32 s24, s31, 0xffff8000
	s_and_b32 s24, s24, 0x10000
	v_add_u32_e32 v189, s24, v231
	v_add_u32_e32 v226, s24, v232
	ds_read_b128 v[158:161], v226
	v_mfma_f32_16x16x32_bf16 v[78:81], v[170:173], v[234:237], v[78:81]
	ds_read_b128 v[154:157], v226 offset:1024
	v_mfma_f32_16x16x32_bf16 v[46:49], v[166:169], v[234:237], v[46:49]
	ds_read_b128 v[150:153], v226 offset:2048
	v_mfma_f32_16x16x32_bf16 v[14:17], v[162:165], v[234:237], v[14:17]
	ds_read_b128 v[146:149], v226 offset:3072
	v_mfma_f32_16x16x32_bf16 v[106:109], v[174:177], v[238:241], v[106:109]
	ds_read_b128 v[130:133], v189
	v_mfma_f32_16x16x32_bf16 v[74:77], v[170:173], v[238:241], v[74:77]
	ds_read_b128 v[134:137], v189 offset:1024
	v_mfma_f32_16x16x32_bf16 v[42:45], v[166:169], v[238:241], v[42:45]
	ds_read_b128 v[138:141], v189 offset:2048
	v_mfma_f32_16x16x32_bf16 v[10:13], v[162:165], v[238:241], v[10:13]
	ds_read_b128 v[142:145], v189 offset:3072
	s_add_i32 s30, s30, 2
	s_add_u32 s20, s20, 0x80
	s_addc_u32 s21, s21, 0
	s_add_i32 s31, s31, 0x10000
	v_mfma_f32_16x16x32_bf16 v[102:105], v[174:177], v[182:185], v[102:105]
	v_mfma_f32_16x16x32_bf16 v[70:73], v[170:173], v[182:185], v[70:73]
	v_mfma_f32_16x16x32_bf16 v[38:41], v[166:169], v[182:185], v[38:41]
	v_mfma_f32_16x16x32_bf16 v[6:9], v[162:165], v[182:185], v[6:9]
	v_mfma_f32_16x16x32_bf16 v[94:97], v[174:177], v[178:181], v[94:97]
	v_mfma_f32_16x16x32_bf16 v[62:65], v[170:173], v[178:181], v[62:65]
	v_mfma_f32_16x16x32_bf16 v[30:33], v[166:169], v[178:181], v[30:33]
	v_mfma_f32_16x16x32_bf16 v[2:5], v[162:165], v[178:181], v[2:5]
	s_cmp_lt_u32 s30, 28
	s_cbranch_scc1 .Lgf_G1x_top
	s_branch .LBB0_645
.Lgr_G1x_entry:
	s_waitcnt vmcnt(4)
	s_waitcnt lgkmcnt(0)
	s_barrier
	v_mfma_f32_16x16x32_bf16 v[126:129], v[130:133], v[158:161], v[126:129]
	v_mfma_f32_16x16x32_bf16 v[98:101], v[134:137], v[158:161], v[98:101]
	s_add_i32 s28, s31, 0xfffe8000
	s_and_b32 s34, s28, 0x10000
	v_add_u32_e32 v170, s34, v233
	ds_read_b128 v[162:165], v170
	v_mfma_f32_16x16x32_bf16 v[66:69], v[138:141], v[158:161], v[66:69]
	ds_read_b128 v[166:169], v170 offset:1024
	v_mfma_f32_16x16x32_bf16 v[34:37], v[142:145], v[158:161], v[34:37]
	ds_read_b128 v[234:237], v170 offset:2048
	v_mfma_f32_16x16x32_bf16 v[122:125], v[130:133], v[154:157], v[122:125]
	ds_read_b128 v[238:241], v170 offset:3072
	s_and_b32 s40, s31, 0x18000
	s_add_i32 s40, s40, s69
	s_mov_b32 m0, s40
	v_mfma_f32_16x16x32_bf16 v[90:93], v[134:137], v[154:157], v[90:93]
	v_mfma_f32_16x16x32_bf16 v[58:61], v[138:141], v[154:157], v[58:61]
	global_load_lds_dwordx4 v188, s[94:95]
	s_add_i32 m0, s40, 0x2000
	v_mfma_f32_16x16x32_bf16 v[26:29], v[142:145], v[154:157], v[26:29]
	v_mfma_f32_16x16x32_bf16 v[118:121], v[130:133], v[150:153], v[118:121]
	v_mfma_f32_16x16x32_bf16 v[86:89], v[134:137], v[150:153], v[86:89]
	global_load_lds_dwordx4 v190, s[94:95]
	s_add_i32 m0, s40, 0x4000
	v_mfma_f32_16x16x32_bf16 v[54:57], v[138:141], v[150:153], v[54:57]
	v_mfma_f32_16x16x32_bf16 v[22:25], v[142:145], v[150:153], v[22:25]
	global_load_lds_dwordx4 v192, s[42:43]
	s_add_i32 m0, s40, 0x6000
	v_mfma_f32_16x16x32_bf16 v[114:117], v[130:133], v[146:149], v[114:117]
	v_mfma_f32_16x16x32_bf16 v[82:85], v[134:137], v[146:149], v[82:85]
	global_load_lds_dwordx4 v194, s[42:43]
	s_add_u32 s94, s94, 64
	s_addc_u32 s95, s95, 0
	s_add_u32 s42, s42, 64
	s_addc_u32 s43, s43, 0
	v_mfma_f32_16x16x32_bf16 v[50:53], v[138:141], v[146:149], v[50:53]
	v_mfma_f32_16x16x32_bf16 v[18:21], v[142:145], v[146:149], v[18:21]
	s_waitcnt vmcnt(4)
	s_waitcnt lgkmcnt(0)
	s_barrier
	v_mfma_f32_16x16x32_bf16 v[110:113], v[130:133], v[162:165], v[110:113]
	s_add_i32 s28, s31, 0xffff0000
	s_and_b32 s35, s28, 0x18000
	v_add_u32_e32 v189, s35, v231
	v_add_u32_e32 v226, s35, v232
	ds_read_b128 v[158:161], v226
	v_mfma_f32_16x16x32_bf16 v[78:81], v[134:137], v[162:165], v[78:81]
	ds_read_b128 v[154:157], v226 offset:1024
	v_mfma_f32_16x16x32_bf16 v[46:49], v[138:141], v[162:165], v[46:49]
	ds_read_b128 v[150:153], v226 offset:2048
	v_mfma_f32_16x16x32_bf16 v[14:17], v[142:145], v[162:165], v[14:17]
	ds_read_b128 v[146:149], v226 offset:3072
	v_mfma_f32_16x16x32_bf16 v[106:109], v[130:133], v[166:169], v[106:109]
	ds_read_b128 v[174:177], v189
	v_mfma_f32_16x16x32_bf16 v[74:77], v[134:137], v[166:169], v[74:77]
	ds_read_b128 v[170:173], v189 offset:1024
	v_mfma_f32_16x16x32_bf16 v[42:45], v[138:141], v[166:169], v[42:45]
	ds_read_b128 v[162:165], v189 offset:3072
	v_mfma_f32_16x16x32_bf16 v[10:13], v[142:145], v[166:169], v[10:13]
	ds_read_b128 v[166:169], v189 offset:2048
	v_mfma_f32_16x16x32_bf16 v[102:105], v[130:133], v[234:237], v[102:105]
	v_mfma_f32_16x16x32_bf16 v[70:73], v[134:137], v[234:237], v[70:73]
	v_mfma_f32_16x16x32_bf16 v[38:41], v[138:141], v[234:237], v[38:41]
	v_mfma_f32_16x16x32_bf16 v[6:9], v[142:145], v[234:237], v[6:9]
	v_mfma_f32_16x16x32_bf16 v[94:97], v[130:133], v[238:241], v[94:97]
	v_mfma_f32_16x16x32_bf16 v[62:65], v[134:137], v[238:241], v[62:65]
	v_mfma_f32_16x16x32_bf16 v[30:33], v[138:141], v[238:241], v[30:33]
	v_mfma_f32_16x16x32_bf16 v[2:5], v[142:145], v[238:241], v[2:5]
	s_waitcnt lgkmcnt(0)
	v_mfma_f32_16x16x32_bf16 v[126:129], v[174:177], v[158:161], v[126:129]
	v_mfma_f32_16x16x32_bf16 v[98:101], v[170:173], v[158:161], v[98:101]
	v_add_u32_e32 v226, s35, v233
	ds_read_b128 v[234:237], v226
	v_mfma_f32_16x16x32_bf16 v[66:69], v[166:169], v[158:161], v[66:69]
	ds_read_b128 v[238:241], v226 offset:1024
	v_mfma_f32_16x16x32_bf16 v[34:37], v[162:165], v[158:161], v[34:37]
	ds_read_b128 v[182:185], v226 offset:2048
	v_mfma_f32_16x16x32_bf16 v[122:125], v[174:177], v[154:157], v[122:125]
	ds_read_b128 v[178:181], v226 offset:3072
	s_add_i32 s40, s34, s69
	s_mov_b32 m0, s40
	v_mfma_f32_16x16x32_bf16 v[90:93], v[170:173], v[154:157], v[90:93]
	v_mfma_f32_16x16x32_bf16 v[58:61], v[166:169], v[154:157], v[58:61]
	global_load_lds_dwordx4 v188, s[94:95]
	s_add_i32 m0, s40, 0x2000
	v_mfma_f32_16x16x32_bf16 v[26:29], v[162:165], v[154:157], v[26:29]
	v_mfma_f32_16x16x32_bf16 v[118:121], v[174:177], v[150:153], v[118:121]
	v_mfma_f32_16x16x32_bf16 v[86:89], v[170:173], v[150:153], v[86:89]
	global_load_lds_dwordx4 v190, s[94:95]
	s_add_i32 m0, s40, 0x4000
	v_mfma_f32_16x16x32_bf16 v[54:57], v[166:169], v[150:153], v[54:57]
	v_mfma_f32_16x16x32_bf16 v[22:25], v[162:165], v[150:153], v[22:25]
	global_load_lds_dwordx4 v192, s[42:43]
	s_add_i32 m0, s40, 0x6000
	v_mfma_f32_16x16x32_bf16 v[114:117], v[174:177], v[146:149], v[114:117]
	v_mfma_f32_16x16x32_bf16 v[82:85], v[170:173], v[146:149], v[82:85]
	global_load_lds_dwordx4 v194, s[42:43]
	s_add_u32 s94, s94, 64
	s_addc_u32 s95, s95, 0
	s_add_u32 s42, s42, 64
	s_addc_u32 s43, s43, 0
	v_mfma_f32_16x16x32_bf16 v[50:53], v[166:169], v[146:149], v[50:53]
	v_mfma_f32_16x16x32_bf16 v[18:21], v[162:165], v[146:149], v[18:21]
.Lgr_G1x_top:
	s_waitcnt vmcnt(4)
	s_waitcnt lgkmcnt(0)
	s_barrier
	v_mfma_f32_16x16x32_bf16 v[110:113], v[174:177], v[234:237], v[110:113]
	s_add_i32 s24, s31, 0xffff8000
	s_and_b32 s24, s24, 0x10000
	v_add_u32_e32 v189, s24, v231
	v_add_u32_e32 v226, s24, v232
	ds_read_b128 v[158:161], v226
	v_mfma_f32_16x16x32_bf16 v[78:81], v[170:173], v[234:237], v[78:81]
	ds_read_b128 v[154:157], v226 offset:1024
	v_mfma_f32_16x16x32_bf16 v[46:49], v[166:169], v[234:237], v[46:49]
	ds_read_b128 v[150:153], v226 offset:2048
	v_mfma_f32_16x16x32_bf16 v[14:17], v[162:165], v[234:237], v[14:17]
	ds_read_b128 v[146:149], v226 offset:3072
	v_mfma_f32_16x16x32_bf16 v[106:109], v[174:177], v[238:241], v[106:109]
	ds_read_b128 v[130:133], v189
	v_mfma_f32_16x16x32_bf16 v[74:77], v[170:173], v[238:241], v[74:77]
	ds_read_b128 v[134:137], v189 offset:1024
	v_mfma_f32_16x16x32_bf16 v[42:45], v[166:169], v[238:241], v[42:45]
	ds_read_b128 v[138:141], v189 offset:2048
	v_mfma_f32_16x16x32_bf16 v[10:13], v[162:165], v[238:241], v[10:13]
	ds_read_b128 v[142:145], v189 offset:3072
	s_add_i32 s30, s30, 2
	s_add_u32 s20, s20, 0x80
	s_addc_u32 s21, s21, 0
	s_add_i32 s31, s31, 0x10000
	v_mfma_f32_16x16x32_bf16 v[102:105], v[174:177], v[182:185], v[102:105]
	v_mfma_f32_16x16x32_bf16 v[70:73], v[170:173], v[182:185], v[70:73]
	v_mfma_f32_16x16x32_bf16 v[38:41], v[166:169], v[182:185], v[38:41]
	v_mfma_f32_16x16x32_bf16 v[6:9], v[162:165], v[182:185], v[6:9]
	v_mfma_f32_16x16x32_bf16 v[94:97], v[174:177], v[178:181], v[94:97]
	v_mfma_f32_16x16x32_bf16 v[62:65], v[170:173], v[178:181], v[62:65]
	v_mfma_f32_16x16x32_bf16 v[30:33], v[166:169], v[178:181], v[30:33]
	v_mfma_f32_16x16x32_bf16 v[2:5], v[162:165], v[178:181], v[2:5]
	s_cmp_lt_u32 s30, 28
	s_cbranch_scc0 .LBB0_645
	s_waitcnt lgkmcnt(0)
	v_mfma_f32_16x16x32_bf16 v[126:129], v[130:133], v[158:161], v[126:129]
	v_mfma_f32_16x16x32_bf16 v[98:101], v[134:137], v[158:161], v[98:101]
	s_add_i32 s28, s31, 0xfffe8000
	s_and_b32 s34, s28, 0x10000
	v_add_u32_e32 v170, s34, v233
	ds_read_b128 v[162:165], v170
	v_mfma_f32_16x16x32_bf16 v[66:69], v[138:141], v[158:161], v[66:69]
	ds_read_b128 v[166:169], v170 offset:1024
	v_mfma_f32_16x16x32_bf16 v[34:37], v[142:145], v[158:161], v[34:37]
	ds_read_b128 v[234:237], v170 offset:2048
	v_mfma_f32_16x16x32_bf16 v[122:125], v[130:133], v[154:157], v[122:125]
	ds_read_b128 v[238:241], v170 offset:3072
	s_and_b32 s40, s31, 0x18000
	s_add_i32 s40, s40, s69
	s_mov_b32 m0, s40
	v_mfma_f32_16x16x32_bf16 v[90:93], v[134:137], v[154:157], v[90:93]
	v_mfma_f32_16x16x32_bf16 v[58:61], v[138:141], v[154:157], v[58:61]
	global_load_lds_dwordx4 v188, s[94:95]
	s_add_i32 m0, s40, 0x2000
	v_mfma_f32_16x16x32_bf16 v[26:29], v[142:145], v[154:157], v[26:29]
	v_mfma_f32_16x16x32_bf16 v[118:121], v[130:133], v[150:153], v[118:121]
	v_mfma_f32_16x16x32_bf16 v[86:89], v[134:137], v[150:153], v[86:89]
	global_load_lds_dwordx4 v190, s[94:95]
	s_add_i32 m0, s40, 0x4000
	v_mfma_f32_16x16x32_bf16 v[54:57], v[138:141], v[150:153], v[54:57]
	v_mfma_f32_16x16x32_bf16 v[22:25], v[142:145], v[150:153], v[22:25]
	global_load_lds_dwordx4 v192, s[42:43]
	s_add_i32 m0, s40, 0x6000
	v_mfma_f32_16x16x32_bf16 v[114:117], v[130:133], v[146:149], v[114:117]
	v_mfma_f32_16x16x32_bf16 v[82:85], v[134:137], v[146:149], v[82:85]
	global_load_lds_dwordx4 v194, s[42:43]
	s_add_u32 s94, s94, 64
	s_addc_u32 s95, s95, 0
	s_add_u32 s42, s42, 64
	s_addc_u32 s43, s43, 0
	v_mfma_f32_16x16x32_bf16 v[50:53], v[138:141], v[146:149], v[50:53]
	v_mfma_f32_16x16x32_bf16 v[18:21], v[142:145], v[146:149], v[18:21]
	s_waitcnt vmcnt(4)
	s_waitcnt lgkmcnt(0)
	s_barrier
	v_mfma_f32_16x16x32_bf16 v[110:113], v[130:133], v[162:165], v[110:113]
	s_add_i32 s28, s31, 0xffff0000
	s_and_b32 s35, s28, 0x18000
	v_add_u32_e32 v189, s35, v231
	v_add_u32_e32 v226, s35, v232
	ds_read_b128 v[158:161], v226
	v_mfma_f32_16x16x32_bf16 v[78:81], v[134:137], v[162:165], v[78:81]
	ds_read_b128 v[154:157], v226 offset:1024
	v_mfma_f32_16x16x32_bf16 v[46:49], v[138:141], v[162:165], v[46:49]
	ds_read_b128 v[150:153], v226 offset:2048
	v_mfma_f32_16x16x32_bf16 v[14:17], v[142:145], v[162:165], v[14:17]
	ds_read_b128 v[146:149], v226 offset:3072
	v_mfma_f32_16x16x32_bf16 v[106:109], v[130:133], v[166:169], v[106:109]
	ds_read_b128 v[174:177], v189
	v_mfma_f32_16x16x32_bf16 v[74:77], v[134:137], v[166:169], v[74:77]
	ds_read_b128 v[170:173], v189 offset:1024
	v_mfma_f32_16x16x32_bf16 v[42:45], v[138:141], v[166:169], v[42:45]
	ds_read_b128 v[162:165], v189 offset:3072
	v_mfma_f32_16x16x32_bf16 v[10:13], v[142:145], v[166:169], v[10:13]
	ds_read_b128 v[166:169], v189 offset:2048
	v_mfma_f32_16x16x32_bf16 v[102:105], v[130:133], v[234:237], v[102:105]
	v_mfma_f32_16x16x32_bf16 v[70:73], v[134:137], v[234:237], v[70:73]
	v_mfma_f32_16x16x32_bf16 v[38:41], v[138:141], v[234:237], v[38:41]
	v_mfma_f32_16x16x32_bf16 v[6:9], v[142:145], v[234:237], v[6:9]
	v_mfma_f32_16x16x32_bf16 v[94:97], v[130:133], v[238:241], v[94:97]
	v_mfma_f32_16x16x32_bf16 v[62:65], v[134:137], v[238:241], v[62:65]
	v_mfma_f32_16x16x32_bf16 v[30:33], v[138:141], v[238:241], v[30:33]
	v_mfma_f32_16x16x32_bf16 v[2:5], v[142:145], v[238:241], v[2:5]
	s_waitcnt lgkmcnt(0)
	v_mfma_f32_16x16x32_bf16 v[126:129], v[174:177], v[158:161], v[126:129]
	v_mfma_f32_16x16x32_bf16 v[98:101], v[170:173], v[158:161], v[98:101]
	v_add_u32_e32 v226, s35, v233
	ds_read_b128 v[234:237], v226
	v_mfma_f32_16x16x32_bf16 v[66:69], v[166:169], v[158:161], v[66:69]
	ds_read_b128 v[238:241], v226 offset:1024
	v_mfma_f32_16x16x32_bf16 v[34:37], v[162:165], v[158:161], v[34:37]
	ds_read_b128 v[182:185], v226 offset:2048
	v_mfma_f32_16x16x32_bf16 v[122:125], v[174:177], v[154:157], v[122:125]
	ds_read_b128 v[178:181], v226 offset:3072
	s_add_i32 s40, s34, s69
	s_mov_b32 m0, s40
	v_mfma_f32_16x16x32_bf16 v[90:93], v[170:173], v[154:157], v[90:93]
	v_mfma_f32_16x16x32_bf16 v[58:61], v[166:169], v[154:157], v[58:61]
	global_load_lds_dwordx4 v188, s[94:95]
	s_add_i32 m0, s40, 0x2000
	v_mfma_f32_16x16x32_bf16 v[26:29], v[162:165], v[154:157], v[26:29]
	v_mfma_f32_16x16x32_bf16 v[118:121], v[174:177], v[150:153], v[118:121]
	v_mfma_f32_16x16x32_bf16 v[86:89], v[170:173], v[150:153], v[86:89]
	global_load_lds_dwordx4 v190, s[94:95]
	s_add_i32 m0, s40, 0x4000
	v_mfma_f32_16x16x32_bf16 v[54:57], v[166:169], v[150:153], v[54:57]
	v_mfma_f32_16x16x32_bf16 v[22:25], v[162:165], v[150:153], v[22:25]
	global_load_lds_dwordx4 v192, s[42:43]
	s_add_i32 m0, s40, 0x6000
	v_mfma_f32_16x16x32_bf16 v[114:117], v[174:177], v[146:149], v[114:117]
	v_mfma_f32_16x16x32_bf16 v[82:85], v[170:173], v[146:149], v[82:85]
	global_load_lds_dwordx4 v194, s[42:43]
	s_add_u32 s94, s94, 64
	s_addc_u32 s95, s95, 0
	s_add_u32 s42, s42, 64
	s_addc_u32 s43, s43, 0
	v_mfma_f32_16x16x32_bf16 v[50:53], v[166:169], v[146:149], v[50:53]
	v_mfma_f32_16x16x32_bf16 v[18:21], v[162:165], v[146:149], v[18:21]
	s_branch .Lgr_G1x_top
